# prep transposes: the 34 (+32 gate) LDS reads of each thread's conv window are issued together and the width-3 conv / silu gate evaluated 4-8 elements in parallel instead of one LDS round trip per elem
# speedup vs baseline: 1.0136x; 1.0136x over previous
; __device__ __forceinline__ void prep_tr_all(const Params& p, LAS unsigned char* lds, int l, int tid, int G) {
;     ...
;                 *(u32x4*)(d + 8 * h4) = (u32x4){w[0], w[1], w[2], w[3]}; }
;         }
;         __syncthreads();
;         if (!more) break;
;         u = un;
;     }
.Lptr_tail:
	s_and_b64 vcc, exec, s[22:23]
	s_mov_b64 s[90:91], s[48:49]
	s_mov_b64 s[96:97], s[44:45]
	s_mov_b32 s50, s34
	s_mov_b32 s27, s63
	s_mov_b32 s26, s24
	global_store_dwordx4 v[44:45], v[66:69], off offset:48
	s_barrier
	s_cbranch_vccnz .LBB0_393

; __device__ __forceinline__ float bf2f(unsigned h) { return __uint_as_float(h << 16); }
; __device__ __forceinline__ float silu_f(float v) { return v * __builtin_amdgcn_rcpf(1.0f + __expf(-v)); }
; __device__ __forceinline__ void prep_tr_all(const Params& p, LAS unsigned char* lds, int l, int tid, int G) {
;     ...
;             const int col = tid >> 2, tc = tid & 3;
;             float w0 = 0.f, w1 = 1.f, w2 = 0.f, cb = 0.f;
;             if (C.mode != 0) { const int ch = C.scol - 1024 + col; const float* cw = p.hy_conv_w + (size_t)l * 3 * 768 + ch; w0 = cw[0]; w1 = cw[768]; w2 = cw[1536]; cb = p.hy_conv_b[l * 768 + ch]; }
;             bf16* d = C.dst + (size_t)col * C.cstride + C.pos0 + 32 * tc;
;             float prev = bf2f(tile[(32 * tc) * 130 + col]), curv = bf2f(tile[(32 * tc + 1) * 130 + col]);
; #pragma unroll
;             for (int h4 = 0; h4 < 4; ++h4) { unsigned w[4];
; #pragma unroll
;                 for (int i = 0; i < 4; ++i) { float o2[2];
; #pragma unroll
;                     for (int e = 0; e < 2; ++e) { const int k = 8 * h4 + 2 * i + e; const float nxt = bf2f(tile[(32 * tc + k + 2) * 130 + col]);
;                         float v = cb + w0 * prev + w1 * curv + w2 * nxt; if (C.mode == 3) v *= silu_f(bf2f(tileg[(32 * tc + k) * 130 + col])); o2[e] = v; prev = curv; curv = nxt; }
.LBB0_329:
	ds_read_u16 v74, v58 offset:0
	ds_read_u16 v75, v58 offset:260
	ds_read_u16 v76, v58 offset:520
	ds_read_u16 v77, v58 offset:780
	ds_read_u16 v78, v58 offset:1040
	ds_read_u16 v79, v58 offset:1300
	ds_read_u16 v80, v58 offset:1560
	ds_read_u16 v81, v58 offset:1820
	ds_read_u16 v82, v58 offset:2080
	ds_read_u16 v83, v58 offset:2340
	ds_read_u16 v84, v58 offset:2600
	ds_read_u16 v85, v58 offset:2860
	ds_read_u16 v86, v58 offset:3120
	ds_read_u16 v87, v58 offset:3380
	ds_read_u16 v88, v58 offset:3640
	s_waitcnt lgkmcnt(14)
	ds_read_u16 v89, v58 offset:3900
	s_waitcnt lgkmcnt(14)
	ds_read_u16 v90, v58 offset:4160
	s_waitcnt lgkmcnt(14)
	ds_read_u16 v91, v58 offset:4420
	s_waitcnt lgkmcnt(14)
	ds_read_u16 v92, v58 offset:4680
	s_waitcnt lgkmcnt(14)
	ds_read_u16 v93, v58 offset:4940
	s_waitcnt lgkmcnt(14)
	ds_read_u16 v94, v58 offset:5200
	s_waitcnt lgkmcnt(14)
	ds_read_u16 v95, v58 offset:5460
	s_waitcnt lgkmcnt(14)
	ds_read_u16 v96, v58 offset:5720
	s_waitcnt lgkmcnt(14)
	ds_read_u16 v97, v58 offset:5980
	s_waitcnt lgkmcnt(14)
	ds_read_u16 v98, v58 offset:6240
	s_waitcnt lgkmcnt(14)
	ds_read_u16 v99, v58 offset:6500
	s_waitcnt lgkmcnt(14)
	ds_read_u16 v100, v58 offset:6760
	s_waitcnt lgkmcnt(14)
	ds_read_u16 v101, v58 offset:7020
	s_waitcnt lgkmcnt(14)
	ds_read_u16 v102, v58 offset:7280
	s_waitcnt lgkmcnt(14)
	ds_read_u16 v103, v58 offset:7540
	s_waitcnt lgkmcnt(14)
	ds_read_u16 v104, v58 offset:7800
	s_waitcnt lgkmcnt(14)
	ds_read_u16 v105, v58 offset:8060
	s_waitcnt lgkmcnt(14)
	ds_read_u16 v106, v58 offset:8320
	s_waitcnt lgkmcnt(14)
	ds_read_u16 v107, v58 offset:8580
	s_and_b64 vcc, exec, s[68:69]
	s_cbranch_vccz .Lptr_a
	s_waitcnt lgkmcnt(14)
	ds_read_u16 v108, v64 offset:33800
	s_waitcnt lgkmcnt(14)
	ds_read_u16 v109, v64 offset:34060
	s_waitcnt lgkmcnt(14)
	ds_read_u16 v110, v64 offset:34320
	s_waitcnt lgkmcnt(14)
	ds_read_u16 v111, v64 offset:34580
	s_waitcnt lgkmcnt(14)
	ds_read_u16 v112, v64 offset:34840
	s_waitcnt lgkmcnt(14)
	ds_read_u16 v113, v64 offset:35100
	s_waitcnt lgkmcnt(14)
	ds_read_u16 v114, v64 offset:35360
	s_waitcnt lgkmcnt(14)
	ds_read_u16 v115, v64 offset:35620
	s_waitcnt lgkmcnt(14)
	ds_read_u16 v116, v64 offset:35880
	s_waitcnt lgkmcnt(14)
	ds_read_u16 v117, v64 offset:36140
	s_waitcnt lgkmcnt(14)
	ds_read_u16 v118, v64 offset:36400
	s_waitcnt lgkmcnt(14)
	ds_read_u16 v119, v64 offset:36660
	s_waitcnt lgkmcnt(14)
	ds_read_u16 v120, v64 offset:36920
	s_waitcnt lgkmcnt(14)
	ds_read_u16 v121, v64 offset:37180
	s_waitcnt lgkmcnt(14)
	ds_read_u16 v122, v64 offset:37440
	s_waitcnt lgkmcnt(14)
	ds_read_u16 v123, v64 offset:37700
	s_waitcnt lgkmcnt(14)
	ds_read_u16 v124, v64 offset:37960
	s_waitcnt lgkmcnt(14)
	ds_read_u16 v125, v64 offset:38220
	s_waitcnt lgkmcnt(14)
	ds_read_u16 v126, v64 offset:38480
	s_waitcnt lgkmcnt(14)
	ds_read_u16 v127, v64 offset:38740
	s_waitcnt lgkmcnt(14)
	ds_read_u16 v128, v64 offset:39000
	s_waitcnt lgkmcnt(14)
	ds_read_u16 v129, v64 offset:39260
	s_waitcnt lgkmcnt(14)
	ds_read_u16 v130, v64 offset:39520
	s_waitcnt lgkmcnt(14)
	ds_read_u16 v131, v64 offset:39780
	s_waitcnt lgkmcnt(14)
	ds_read_u16 v132, v64 offset:40040
	s_waitcnt lgkmcnt(14)
	ds_read_u16 v133, v64 offset:40300
	s_waitcnt lgkmcnt(14)
	ds_read_u16 v134, v64 offset:40560
	s_waitcnt lgkmcnt(14)
	ds_read_u16 v135, v64 offset:40820
	s_waitcnt lgkmcnt(14)
	ds_read_u16 v136, v64 offset:41080
	s_waitcnt lgkmcnt(14)
	ds_read_u16 v137, v64 offset:41340
	s_waitcnt lgkmcnt(14)
	ds_read_u16 v138, v64 offset:41600
	s_waitcnt lgkmcnt(14)
	ds_read_u16 v139, v64 offset:41860
.Lptr_a:
	v_mad_u64_u32 v[44:45], s[26:27], s90, v40, 0
	v_mov_b32_e32 v50, v45
	v_mad_u64_u32 v[50:51], s[26:27], s91, v40, v[50:51]
	v_mov_b32_e32 v45, v50
	v_lshl_add_u64 v[44:45], v[44:45], 1, s[96:97]
	s_ashr_i32 s51, s50, 31
	v_lshl_add_u64 v[44:45], s[50:51], 1, v[44:45]
	v_lshl_add_u64 v[44:45], v[44:45], 0, v[0:1]
	s_waitcnt lgkmcnt(0)
	v_lshlrev_b32_e32 v74, 16, v74
	v_lshlrev_b32_e32 v75, 16, v75
	v_lshlrev_b32_e32 v76, 16, v76
	v_lshlrev_b32_e32 v77, 16, v77
	v_lshlrev_b32_e32 v78, 16, v78
	v_lshlrev_b32_e32 v79, 16, v79
	v_lshlrev_b32_e32 v80, 16, v80
	v_lshlrev_b32_e32 v81, 16, v81
	v_lshlrev_b32_e32 v82, 16, v82
	v_lshlrev_b32_e32 v83, 16, v83
	v_lshlrev_b32_e32 v84, 16, v84
	v_lshlrev_b32_e32 v85, 16, v85
	v_lshlrev_b32_e32 v86, 16, v86
	v_lshlrev_b32_e32 v87, 16, v87
	v_lshlrev_b32_e32 v88, 16, v88
	v_lshlrev_b32_e32 v89, 16, v89
	v_lshlrev_b32_e32 v90, 16, v90
	v_lshlrev_b32_e32 v91, 16, v91
	v_lshlrev_b32_e32 v92, 16, v92
	v_lshlrev_b32_e32 v93, 16, v93
	v_lshlrev_b32_e32 v94, 16, v94
	v_lshlrev_b32_e32 v95, 16, v95
	v_lshlrev_b32_e32 v96, 16, v96
	v_lshlrev_b32_e32 v97, 16, v97
	v_lshlrev_b32_e32 v98, 16, v98
	v_lshlrev_b32_e32 v99, 16, v99
	v_lshlrev_b32_e32 v100, 16, v100
	v_lshlrev_b32_e32 v101, 16, v101
	v_lshlrev_b32_e32 v102, 16, v102
	v_lshlrev_b32_e32 v103, 16, v103
	v_lshlrev_b32_e32 v104, 16, v104
	v_lshlrev_b32_e32 v105, 16, v105
	v_lshlrev_b32_e32 v106, 16, v106
	v_lshlrev_b32_e32 v107, 16, v107
	s_and_b64 vcc, exec, s[68:69]
	s_cbranch_vccz .Lptr_b
; __device__ __forceinline__ float bf2f(unsigned h) { return __uint_as_float(h << 16); }
; __device__ __forceinline__ unsigned pk2(float lo, float hi) { f32x2_t v = {lo, hi}; bf16x2_t b = __builtin_convertvector(v, bf16x2_t); return __builtin_bit_cast(unsigned, b); }
; __device__ __forceinline__ float silu_f(float v) { return v * __builtin_amdgcn_rcpf(1.0f + __expf(-v)); }
; __device__ __forceinline__ void prep_tr_all(const Params& p, LAS unsigned char* lds, int l, int tid, int G) {
;     ...
;                     for (int e = 0; e < 2; ++e) { const int k = 8 * h4 + 2 * i + e; const float nxt = bf2f(tile[(32 * tc + k + 2) * 130 + col]);
;                         float v = cb + w0 * prev + w1 * curv + w2 * nxt; if (C.mode == 3) v *= silu_f(bf2f(tileg[(32 * tc + k) * 130 + col])); o2[e] = v; prev = curv; curv = nxt; }
;                     w[i] = pk2(o2[0], o2[1]); }
	v_lshlrev_b32_e32 v108, 16, v108
	v_lshlrev_b32_e32 v109, 16, v109
	v_lshlrev_b32_e32 v110, 16, v110
	v_lshlrev_b32_e32 v111, 16, v111
	v_lshlrev_b32_e32 v112, 16, v112
	v_lshlrev_b32_e32 v113, 16, v113
	v_lshlrev_b32_e32 v114, 16, v114
	v_lshlrev_b32_e32 v115, 16, v115
	v_mul_f32_e32 v66, 0xbfb8aa3b, v108
	v_mul_f32_e32 v67, 0xbfb8aa3b, v109
	v_mul_f32_e32 v68, 0xbfb8aa3b, v110
	v_mul_f32_e32 v69, 0xbfb8aa3b, v111
	v_mul_f32_e32 v70, 0xbfb8aa3b, v112
	v_mul_f32_e32 v71, 0xbfb8aa3b, v113
	v_mul_f32_e32 v72, 0xbfb8aa3b, v114
	v_mul_f32_e32 v73, 0xbfb8aa3b, v115
	v_exp_f32_e32 v66, v66
	v_exp_f32_e32 v67, v67
	v_exp_f32_e32 v68, v68
	v_exp_f32_e32 v69, v69
	v_exp_f32_e32 v70, v70
	v_exp_f32_e32 v71, v71
	v_exp_f32_e32 v72, v72
	v_exp_f32_e32 v73, v73
	v_add_f32_e32 v66, 1.0, v66
	v_add_f32_e32 v67, 1.0, v67
	v_add_f32_e32 v68, 1.0, v68
	v_add_f32_e32 v69, 1.0, v69
	v_add_f32_e32 v70, 1.0, v70
	v_add_f32_e32 v71, 1.0, v71
	v_add_f32_e32 v72, 1.0, v72
	v_add_f32_e32 v73, 1.0, v73
	v_rcp_f32_e32 v66, v66
	v_rcp_f32_e32 v67, v67
	v_rcp_f32_e32 v68, v68
	v_rcp_f32_e32 v69, v69
	v_rcp_f32_e32 v70, v70
	v_rcp_f32_e32 v71, v71
	v_rcp_f32_e32 v72, v72
	v_rcp_f32_e32 v73, v73
	v_mul_f32_e32 v108, v66, v108
	v_mul_f32_e32 v109, v67, v109
	v_mul_f32_e32 v110, v68, v110
	v_mul_f32_e32 v111, v69, v111
	v_mul_f32_e32 v112, v70, v112
	v_mul_f32_e32 v113, v71, v113
	v_mul_f32_e32 v114, v72, v114
	v_mul_f32_e32 v115, v73, v115
	v_lshlrev_b32_e32 v116, 16, v116
	v_lshlrev_b32_e32 v117, 16, v117
	v_lshlrev_b32_e32 v118, 16, v118
	v_lshlrev_b32_e32 v119, 16, v119
	v_lshlrev_b32_e32 v120, 16, v120
	v_lshlrev_b32_e32 v121, 16, v121
	v_lshlrev_b32_e32 v122, 16, v122
	v_lshlrev_b32_e32 v123, 16, v123
	v_mul_f32_e32 v66, 0xbfb8aa3b, v116
	v_mul_f32_e32 v67, 0xbfb8aa3b, v117
	v_mul_f32_e32 v68, 0xbfb8aa3b, v118
	v_mul_f32_e32 v69, 0xbfb8aa3b, v119
	v_mul_f32_e32 v70, 0xbfb8aa3b, v120
	v_mul_f32_e32 v71, 0xbfb8aa3b, v121
	v_mul_f32_e32 v72, 0xbfb8aa3b, v122
	v_mul_f32_e32 v73, 0xbfb8aa3b, v123
	v_exp_f32_e32 v66, v66
	v_exp_f32_e32 v67, v67
	v_exp_f32_e32 v68, v68
	v_exp_f32_e32 v69, v69
	v_exp_f32_e32 v70, v70
	v_exp_f32_e32 v71, v71
	v_exp_f32_e32 v72, v72
	v_exp_f32_e32 v73, v73
	v_add_f32_e32 v66, 1.0, v66
	v_add_f32_e32 v67, 1.0, v67
	v_add_f32_e32 v68, 1.0, v68
	v_add_f32_e32 v69, 1.0, v69
	v_add_f32_e32 v70, 1.0, v70
	v_add_f32_e32 v71, 1.0, v71
	v_add_f32_e32 v72, 1.0, v72
	v_add_f32_e32 v73, 1.0, v73
	v_rcp_f32_e32 v66, v66
	v_rcp_f32_e32 v67, v67
	v_rcp_f32_e32 v68, v68
	v_rcp_f32_e32 v69, v69
	v_rcp_f32_e32 v70, v70
	v_rcp_f32_e32 v71, v71
	v_rcp_f32_e32 v72, v72
	v_rcp_f32_e32 v73, v73
	v_mul_f32_e32 v116, v66, v116
	v_mul_f32_e32 v117, v67, v117
	v_mul_f32_e32 v118, v68, v118
	v_mul_f32_e32 v119, v69, v119
	v_mul_f32_e32 v120, v70, v120
	v_mul_f32_e32 v121, v71, v121
	v_mul_f32_e32 v122, v72, v122
	v_mul_f32_e32 v123, v73, v123
	v_lshlrev_b32_e32 v124, 16, v124
	v_lshlrev_b32_e32 v125, 16, v125
	v_lshlrev_b32_e32 v126, 16, v126
	v_lshlrev_b32_e32 v127, 16, v127
	v_lshlrev_b32_e32 v128, 16, v128
	v_lshlrev_b32_e32 v129, 16, v129
	v_lshlrev_b32_e32 v130, 16, v130
	v_lshlrev_b32_e32 v131, 16, v131
	v_mul_f32_e32 v66, 0xbfb8aa3b, v124
	v_mul_f32_e32 v67, 0xbfb8aa3b, v125
	v_mul_f32_e32 v68, 0xbfb8aa3b, v126
	v_mul_f32_e32 v69, 0xbfb8aa3b, v127
	v_mul_f32_e32 v70, 0xbfb8aa3b, v128
	v_mul_f32_e32 v71, 0xbfb8aa3b, v129
	v_mul_f32_e32 v72, 0xbfb8aa3b, v130
	v_mul_f32_e32 v73, 0xbfb8aa3b, v131
	v_exp_f32_e32 v66, v66
	v_exp_f32_e32 v67, v67
	v_exp_f32_e32 v68, v68
	v_exp_f32_e32 v69, v69
	v_exp_f32_e32 v70, v70
	v_exp_f32_e32 v71, v71
	v_exp_f32_e32 v72, v72
	v_exp_f32_e32 v73, v73
	v_add_f32_e32 v66, 1.0, v66
	v_add_f32_e32 v67, 1.0, v67
	v_add_f32_e32 v68, 1.0, v68
	v_add_f32_e32 v69, 1.0, v69
	v_add_f32_e32 v70, 1.0, v70
	v_add_f32_e32 v71, 1.0, v71
	v_add_f32_e32 v72, 1.0, v72
	v_add_f32_e32 v73, 1.0, v73
	v_rcp_f32_e32 v66, v66
	v_rcp_f32_e32 v67, v67
	v_rcp_f32_e32 v68, v68
	v_rcp_f32_e32 v69, v69
	v_rcp_f32_e32 v70, v70
	v_rcp_f32_e32 v71, v71
	v_rcp_f32_e32 v72, v72
	v_rcp_f32_e32 v73, v73
	v_mul_f32_e32 v124, v66, v124
	v_mul_f32_e32 v125, v67, v125
	v_mul_f32_e32 v126, v68, v126
	v_mul_f32_e32 v127, v69, v127
	v_mul_f32_e32 v128, v70, v128
	v_mul_f32_e32 v129, v71, v129
	v_mul_f32_e32 v130, v72, v130
	v_mul_f32_e32 v131, v73, v131
	v_lshlrev_b32_e32 v132, 16, v132
	v_lshlrev_b32_e32 v133, 16, v133
	v_lshlrev_b32_e32 v134, 16, v134
	v_lshlrev_b32_e32 v135, 16, v135
	v_lshlrev_b32_e32 v136, 16, v136
	v_lshlrev_b32_e32 v137, 16, v137
	v_lshlrev_b32_e32 v138, 16, v138
	v_lshlrev_b32_e32 v139, 16, v139
	v_mul_f32_e32 v66, 0xbfb8aa3b, v132
	v_mul_f32_e32 v67, 0xbfb8aa3b, v133
	v_mul_f32_e32 v68, 0xbfb8aa3b, v134
	v_mul_f32_e32 v69, 0xbfb8aa3b, v135
	v_mul_f32_e32 v70, 0xbfb8aa3b, v136
	v_mul_f32_e32 v71, 0xbfb8aa3b, v137
	v_mul_f32_e32 v72, 0xbfb8aa3b, v138
	v_mul_f32_e32 v73, 0xbfb8aa3b, v139
	v_exp_f32_e32 v66, v66
	v_exp_f32_e32 v67, v67
	v_exp_f32_e32 v68, v68
	v_exp_f32_e32 v69, v69
	v_exp_f32_e32 v70, v70
	v_exp_f32_e32 v71, v71
	v_exp_f32_e32 v72, v72
	v_exp_f32_e32 v73, v73
	v_add_f32_e32 v66, 1.0, v66
	v_add_f32_e32 v67, 1.0, v67
	v_add_f32_e32 v68, 1.0, v68
	v_add_f32_e32 v69, 1.0, v69
	v_add_f32_e32 v70, 1.0, v70
	v_add_f32_e32 v71, 1.0, v71
	v_add_f32_e32 v72, 1.0, v72
	v_add_f32_e32 v73, 1.0, v73
	v_rcp_f32_e32 v66, v66
	v_rcp_f32_e32 v67, v67
	v_rcp_f32_e32 v68, v68
	v_rcp_f32_e32 v69, v69
	v_rcp_f32_e32 v70, v70
	v_rcp_f32_e32 v71, v71
	v_rcp_f32_e32 v72, v72
	v_rcp_f32_e32 v73, v73
	v_mul_f32_e32 v132, v66, v132
	v_mul_f32_e32 v133, v67, v133
	v_mul_f32_e32 v134, v68, v134
	v_mul_f32_e32 v135, v69, v135
	v_mul_f32_e32 v136, v70, v136
	v_mul_f32_e32 v137, v71, v137
	v_mul_f32_e32 v138, v72, v138
	v_mul_f32_e32 v139, v73, v139
; __device__ __forceinline__ float bf2f(unsigned h) { return __uint_as_float(h << 16); }
; __device__ __forceinline__ unsigned pk2(float lo, float hi) { f32x2_t v = {lo, hi}; bf16x2_t b = __builtin_convertvector(v, bf16x2_t); return __builtin_bit_cast(unsigned, b); }
; __device__ __forceinline__ float silu_f(float v) { return v * __builtin_amdgcn_rcpf(1.0f + __expf(-v)); }
; __device__ __forceinline__ void prep_tr_all(const Params& p, LAS unsigned char* lds, int l, int tid, int G) {
;     ...
;                     for (int e = 0; e < 2; ++e) { const int k = 8 * h4 + 2 * i + e; const float nxt = bf2f(tile[(32 * tc + k + 2) * 130 + col]);
;                         float v = cb + w0 * prev + w1 * curv + w2 * nxt; if (C.mode == 3) v *= silu_f(bf2f(tileg[(32 * tc + k) * 130 + col])); o2[e] = v; prev = curv; curv = nxt; }
;                     w[i] = pk2(o2[0], o2[1]); }
;                 *(u32x4*)(d + 8 * h4) = (u32x4){w[0], w[1], w[2], w[3]}; }
.Lptr_b:
	s_waitcnt vmcnt(0)
	v_mul_f32_e32 v66, v42, v75
	v_mul_f32_e32 v67, v42, v76
	v_mul_f32_e32 v68, v42, v77
	v_mul_f32_e32 v69, v42, v78
	v_mul_f32_e32 v70, v43, v76
	v_mul_f32_e32 v71, v43, v77
	v_mul_f32_e32 v72, v43, v78
	v_mul_f32_e32 v73, v43, v79
	v_fma_f32 v74, v39, v74, v65
	v_fma_f32 v75, v39, v75, v65
	v_fma_f32 v76, v39, v76, v65
	v_fma_f32 v77, v39, v77, v65
	v_add_f32_e32 v74, v74, v66
	v_add_f32_e32 v75, v75, v67
	v_add_f32_e32 v76, v76, v68
	v_add_f32_e32 v77, v77, v69
	v_add_f32_e32 v74, v74, v70
	v_add_f32_e32 v75, v75, v71
	v_add_f32_e32 v76, v76, v72
	v_add_f32_e32 v77, v77, v73
	v_mul_f32_e32 v66, v42, v79
	v_mul_f32_e32 v67, v42, v80
	v_mul_f32_e32 v68, v42, v81
	v_mul_f32_e32 v69, v42, v82
	v_mul_f32_e32 v70, v43, v80
	v_mul_f32_e32 v71, v43, v81
	v_mul_f32_e32 v72, v43, v82
	v_mul_f32_e32 v73, v43, v83
	v_fma_f32 v78, v39, v78, v65
	v_fma_f32 v79, v39, v79, v65
	v_fma_f32 v80, v39, v80, v65
	v_fma_f32 v81, v39, v81, v65
	v_add_f32_e32 v78, v78, v66
	v_add_f32_e32 v79, v79, v67
	v_add_f32_e32 v80, v80, v68
	v_add_f32_e32 v81, v81, v69
	v_add_f32_e32 v78, v78, v70
	v_add_f32_e32 v79, v79, v71
	v_add_f32_e32 v80, v80, v72
	v_add_f32_e32 v81, v81, v73
	v_mul_f32_e32 v66, v42, v83
	v_mul_f32_e32 v67, v42, v84
	v_mul_f32_e32 v68, v42, v85
	v_mul_f32_e32 v69, v42, v86
	v_mul_f32_e32 v70, v43, v84
	v_mul_f32_e32 v71, v43, v85
	v_mul_f32_e32 v72, v43, v86
	v_mul_f32_e32 v73, v43, v87
	v_fma_f32 v82, v39, v82, v65
	v_fma_f32 v83, v39, v83, v65
	v_fma_f32 v84, v39, v84, v65
	v_fma_f32 v85, v39, v85, v65
	v_add_f32_e32 v82, v82, v66
	v_add_f32_e32 v83, v83, v67
	v_add_f32_e32 v84, v84, v68
	v_add_f32_e32 v85, v85, v69
	v_add_f32_e32 v82, v82, v70
	v_add_f32_e32 v83, v83, v71
	v_add_f32_e32 v84, v84, v72
	v_add_f32_e32 v85, v85, v73
	v_mul_f32_e32 v66, v42, v87
	v_mul_f32_e32 v67, v42, v88
	v_mul_f32_e32 v68, v42, v89
	v_mul_f32_e32 v69, v42, v90
	v_mul_f32_e32 v70, v43, v88
	v_mul_f32_e32 v71, v43, v89
	v_mul_f32_e32 v72, v43, v90
	v_mul_f32_e32 v73, v43, v91
	v_fma_f32 v86, v39, v86, v65
	v_fma_f32 v87, v39, v87, v65
	v_fma_f32 v88, v39, v88, v65
	v_fma_f32 v89, v39, v89, v65
	v_add_f32_e32 v86, v86, v66
	v_add_f32_e32 v87, v87, v67
	v_add_f32_e32 v88, v88, v68
	v_add_f32_e32 v89, v89, v69
	v_add_f32_e32 v86, v86, v70
	v_add_f32_e32 v87, v87, v71
	v_add_f32_e32 v88, v88, v72
	v_add_f32_e32 v89, v89, v73
	v_mul_f32_e32 v66, v42, v91
	v_mul_f32_e32 v67, v42, v92
	v_mul_f32_e32 v68, v42, v93
	v_mul_f32_e32 v69, v42, v94
	v_mul_f32_e32 v70, v43, v92
	v_mul_f32_e32 v71, v43, v93
	v_mul_f32_e32 v72, v43, v94
	v_mul_f32_e32 v73, v43, v95
	v_fma_f32 v90, v39, v90, v65
	v_fma_f32 v91, v39, v91, v65
	v_fma_f32 v92, v39, v92, v65
	v_fma_f32 v93, v39, v93, v65
	v_add_f32_e32 v90, v90, v66
	v_add_f32_e32 v91, v91, v67
	v_add_f32_e32 v92, v92, v68
	v_add_f32_e32 v93, v93, v69
	v_add_f32_e32 v90, v90, v70
	v_add_f32_e32 v91, v91, v71
	v_add_f32_e32 v92, v92, v72
	v_add_f32_e32 v93, v93, v73
	v_mul_f32_e32 v66, v42, v95
	v_mul_f32_e32 v67, v42, v96
	v_mul_f32_e32 v68, v42, v97
	v_mul_f32_e32 v69, v42, v98
	v_mul_f32_e32 v70, v43, v96
	v_mul_f32_e32 v71, v43, v97
	v_mul_f32_e32 v72, v43, v98
	v_mul_f32_e32 v73, v43, v99
	v_fma_f32 v94, v39, v94, v65
	v_fma_f32 v95, v39, v95, v65
	v_fma_f32 v96, v39, v96, v65
	v_fma_f32 v97, v39, v97, v65
	v_add_f32_e32 v94, v94, v66
	v_add_f32_e32 v95, v95, v67
	v_add_f32_e32 v96, v96, v68
	v_add_f32_e32 v97, v97, v69
	v_add_f32_e32 v94, v94, v70
	v_add_f32_e32 v95, v95, v71
	v_add_f32_e32 v96, v96, v72
	v_add_f32_e32 v97, v97, v73
	v_mul_f32_e32 v66, v42, v99
	v_mul_f32_e32 v67, v42, v100
	v_mul_f32_e32 v68, v42, v101
	v_mul_f32_e32 v69, v42, v102
	v_mul_f32_e32 v70, v43, v100
	v_mul_f32_e32 v71, v43, v101
	v_mul_f32_e32 v72, v43, v102
	v_mul_f32_e32 v73, v43, v103
	v_fma_f32 v98, v39, v98, v65
	v_fma_f32 v99, v39, v99, v65
	v_fma_f32 v100, v39, v100, v65
	v_fma_f32 v101, v39, v101, v65
	v_add_f32_e32 v98, v98, v66
	v_add_f32_e32 v99, v99, v67
	v_add_f32_e32 v100, v100, v68
	v_add_f32_e32 v101, v101, v69
	v_add_f32_e32 v98, v98, v70
	v_add_f32_e32 v99, v99, v71
	v_add_f32_e32 v100, v100, v72
	v_add_f32_e32 v101, v101, v73
	v_mul_f32_e32 v66, v42, v103
	v_mul_f32_e32 v67, v42, v104
	v_mul_f32_e32 v68, v42, v105
	v_mul_f32_e32 v69, v42, v106
	v_mul_f32_e32 v70, v43, v104
	v_mul_f32_e32 v71, v43, v105
	v_mul_f32_e32 v72, v43, v106
	v_mul_f32_e32 v73, v43, v107
	v_fma_f32 v102, v39, v102, v65
	v_fma_f32 v103, v39, v103, v65
	v_fma_f32 v104, v39, v104, v65
	v_fma_f32 v105, v39, v105, v65
	v_add_f32_e32 v102, v102, v66
	v_add_f32_e32 v103, v103, v67
	v_add_f32_e32 v104, v104, v68
	v_add_f32_e32 v105, v105, v69
	v_add_f32_e32 v102, v102, v70
	v_add_f32_e32 v103, v103, v71
	v_add_f32_e32 v104, v104, v72
	v_add_f32_e32 v105, v105, v73
	s_and_b64 vcc, exec, s[68:69]
	s_cbranch_vccz .Lptr_c
	v_mul_f32_e32 v74, v74, v108
	v_mul_f32_e32 v75, v75, v109
	v_mul_f32_e32 v76, v76, v110
	v_mul_f32_e32 v77, v77, v111
	v_mul_f32_e32 v78, v78, v112
	v_mul_f32_e32 v79, v79, v113
	v_mul_f32_e32 v80, v80, v114
	v_mul_f32_e32 v81, v81, v115
	v_mul_f32_e32 v82, v82, v116
	v_mul_f32_e32 v83, v83, v117
	v_mul_f32_e32 v84, v84, v118
	v_mul_f32_e32 v85, v85, v119
	v_mul_f32_e32 v86, v86, v120
	v_mul_f32_e32 v87, v87, v121
	v_mul_f32_e32 v88, v88, v122
	v_mul_f32_e32 v89, v89, v123
	v_mul_f32_e32 v90, v90, v124
	v_mul_f32_e32 v91, v91, v125
	v_mul_f32_e32 v92, v92, v126
	v_mul_f32_e32 v93, v93, v127
	v_mul_f32_e32 v94, v94, v128
	v_mul_f32_e32 v95, v95, v129
	v_mul_f32_e32 v96, v96, v130
	v_mul_f32_e32 v97, v97, v131
	v_mul_f32_e32 v98, v98, v132
	v_mul_f32_e32 v99, v99, v133
	v_mul_f32_e32 v100, v100, v134
	v_mul_f32_e32 v101, v101, v135
	v_mul_f32_e32 v102, v102, v136
	v_mul_f32_e32 v103, v103, v137
	v_mul_f32_e32 v104, v104, v138
	v_mul_f32_e32 v105, v105, v139
.Lptr_c:
	v_cvt_pk_bf16_f32 v70, v74, v75
	v_cvt_pk_bf16_f32 v71, v76, v77
	v_cvt_pk_bf16_f32 v72, v78, v79
	v_cvt_pk_bf16_f32 v73, v80, v81
	global_store_dwordx4 v[44:45], v[70:73], off
	v_cvt_pk_bf16_f32 v140, v82, v83
	v_cvt_pk_bf16_f32 v141, v84, v85
	v_cvt_pk_bf16_f32 v142, v86, v87
	v_cvt_pk_bf16_f32 v143, v88, v89
	global_store_dwordx4 v[44:45], v[140:143], off offset:16
	v_cvt_pk_bf16_f32 v108, v90, v91
	v_cvt_pk_bf16_f32 v109, v92, v93
	v_cvt_pk_bf16_f32 v110, v94, v95
	v_cvt_pk_bf16_f32 v111, v96, v97
	global_store_dwordx4 v[44:45], v[108:111], off offset:32
	v_cvt_pk_bf16_f32 v66, v98, v99
	v_cvt_pk_bf16_f32 v67, v100, v101
	v_cvt_pk_bf16_f32 v68, v102, v103
	v_cvt_pk_bf16_f32 v69, v104, v105
	s_branch .Lptr_tail
.LBB0_393:
	s_nop 0
	s_nop 0
	s_nop 0
	s_nop 0
	s_nop 0
	s_nop 0
	s_nop 0
	s_nop 0
	s_nop 0
	s_nop 0
	s_nop 0
	s_nop 0
	s_nop 0
	s_nop 0
	s_nop 0
	s_nop 0
	s_nop 0
	s_nop 0
	s_nop 0
	s_nop 0
	s_nop 0
	s_nop 0
	s_nop 0
	s_nop 0
	s_nop 0
	s_nop 0
	s_nop 0
	s_nop 0
	s_nop 0
	s_nop 0
	s_nop 0
	s_mov_b64 s[0:1], 0
